# row sum-of-squares partials snapped to 2^-7 grid so f32 atomic accumulation is exact and launch-to-launch deterministic
# baseline (speedup 1.0000x reference)
; __device__ __forceinline__ unsigned cvt_pk_bf16(float lo, float hi) { unsigned r; asm volatile("v_cvt_pk_bf16_f32 %0, %1, %2" : "=v"(r) : "v"(lo), "v"(hi)); return r; }
;     __device__ __forceinline__ void operator()(const f32x4 (&acc)[2][2][4][2], const Unit& u, int wr, int wc, int fr, int fq) const {
;     ...
;             for (int m = 0; m < 4; ++m) { const int row = u.pm * BM + ai * HALF + wr * 64 + m * 16 + fr; const size_t off = (size_t)row * ldc + col0;
;                 float ss = 0.f;
; #pragma unroll
;                 for (int bj = 0; bj < 2; ++bj)
; #pragma unroll
;                     for (int n = 0; n < 2; ++n) { f32x4 bs;
;                         if (BASE_BF16) { const u32x2 t = *(const u32x2*)((const bf16_t*)base + off + bj * HALF + n * 16);
;                             bs = (f32x4){__builtin_bit_cast(float, t.x << 16), __builtin_bit_cast(float, t.x & 0xffff0000u), __builtin_bit_cast(float, t.y << 16), __builtin_bit_cast(float, t.y & 0xffff0000u)}; }
;                         else bs = *(const f32x4*)((const float*)base + off + bj * HALF + n * 16);
;                         const f32x4 v = bs + acc[ai][bj][m][n] * scale;
;                         u32x2 w; w.x = cvt_pk_bf16(v[0], v[1]); w.y = cvt_pk_bf16(v[2], v[3]);
;                         *(u32x2*)(xn + off + bj * HALF + n * 16) = w;
;                         ss += (v[0] * v[0] + v[1] * v[1]) + (v[2] * v[2] + v[3] * v[3]); }
.LBB0_310:
	s_waitcnt vmcnt(8)
	v_pk_fma_f32 v[166:167], v[126:127], 0.5, v[166:167] op_sel_hi:[1,0,1]
	v_pk_fma_f32 v[164:165], v[124:125], 0.5, v[164:165] op_sel_hi:[1,0,1]
	v_pk_fma_f32 v[170:171], v[122:123], 0.5, v[170:171] op_sel_hi:[1,0,1]
	v_pk_fma_f32 v[168:169], v[120:121], 0.5, v[168:169] op_sel_hi:[1,0,1]
	v_pk_fma_f32 v[174:175], v[118:119], 0.5, v[174:175] op_sel_hi:[1,0,1]
	v_pk_fma_f32 v[172:173], v[116:117], 0.5, v[172:173] op_sel_hi:[1,0,1]
	v_pk_fma_f32 v[178:179], v[114:115], 0.5, v[178:179] op_sel_hi:[1,0,1]
	v_pk_fma_f32 v[176:177], v[112:113], 0.5, v[176:177] op_sel_hi:[1,0,1]
	v_mov_b32_e32 v214, v142
	v_ashrrev_i32_e32 v215, 31, v214
	v_lshlrev_b64 v[216:217], 11, v[214:215]
	v_lshl_add_u64 v[216:217], v[216:217], 0, v[140:141]
	v_lshl_add_u64 v[218:219], v[216:217], 1, s[76:77]
	v_cvt_pk_bf16_f32 v124, v164, v165
	v_cvt_pk_bf16_f32 v125, v166, v167
	global_store_dwordx2 v[218:219], v[124:125], off
	v_mul_f32_e32 v221, v165, v165
	v_mul_f32_e32 v162, v167, v167
	v_fmac_f32_e32 v221, v164, v164
	v_fmac_f32_e32 v162, v166, v166
	v_add_f32_e32 v220, v221, v162
	v_cvt_pk_bf16_f32 v120, v168, v169
	v_cvt_pk_bf16_f32 v121, v170, v171
	global_store_dwordx2 v[218:219], v[120:121], off offset:32
	v_mul_f32_e32 v221, v169, v169
	v_mul_f32_e32 v162, v171, v171
	v_fmac_f32_e32 v221, v168, v168
	v_fmac_f32_e32 v162, v170, v170
	v_add_f32_e32 v221, v221, v162
	v_add_f32_e32 v220, v220, v221
	v_cvt_pk_bf16_f32 v116, v172, v173
	v_cvt_pk_bf16_f32 v117, v174, v175
	global_store_dwordx2 v[218:219], v[116:117], off offset:256
	v_mul_f32_e32 v221, v173, v173
	v_mul_f32_e32 v162, v175, v175
	v_fmac_f32_e32 v221, v172, v172
	v_fmac_f32_e32 v162, v174, v174
	v_add_f32_e32 v221, v221, v162
	v_add_f32_e32 v220, v220, v221
	v_cvt_pk_bf16_f32 v112, v176, v177
	v_cvt_pk_bf16_f32 v113, v178, v179
	global_store_dwordx2 v[218:219], v[112:113], off offset:288
	v_mul_f32_e32 v221, v177, v177
	v_mul_f32_e32 v162, v179, v179
	v_fmac_f32_e32 v221, v176, v176
	v_fmac_f32_e32 v162, v178, v178
	v_add_f32_e32 v221, v221, v162
	v_add_f32_e32 v160, v220, v221
	v_add_u32_e32 v152, 48, v142
	v_ashrrev_i32_e32 v153, 31, v152
	v_lshlrev_b64 v[154:155], 11, v[152:153]
	v_lshl_add_u64 v[154:155], v[154:155], 0, v[140:141]
	v_lshl_add_u64 v[156:157], v[154:155], 2, s[0:1]
	global_load_dwordx4 v[112:115], v[156:157], off
	global_load_dwordx4 v[116:119], v[156:157], off offset:64
	global_load_dwordx4 v[120:123], v[156:157], off offset:512
	global_load_dwordx4 v[124:127], v[156:157], off offset:576
	s_waitcnt vmcnt(12)
	v_pk_fma_f32 v[182:183], v[110:111], 0.5, v[182:183] op_sel_hi:[1,0,1]
	v_pk_fma_f32 v[180:181], v[108:109], 0.5, v[180:181] op_sel_hi:[1,0,1]
	v_pk_fma_f32 v[186:187], v[106:107], 0.5, v[186:187] op_sel_hi:[1,0,1]
	v_pk_fma_f32 v[184:185], v[104:105], 0.5, v[184:185] op_sel_hi:[1,0,1]
	v_pk_fma_f32 v[190:191], v[102:103], 0.5, v[190:191] op_sel_hi:[1,0,1]
	v_pk_fma_f32 v[188:189], v[100:101], 0.5, v[188:189] op_sel_hi:[1,0,1]
	v_pk_fma_f32 v[194:195], v[98:99], 0.5, v[194:195] op_sel_hi:[1,0,1]
	v_pk_fma_f32 v[192:193], v[96:97], 0.5, v[192:193] op_sel_hi:[1,0,1]
	v_add_u32_e32 v214, 16, v142
	v_ashrrev_i32_e32 v215, 31, v214
	v_lshlrev_b64 v[216:217], 11, v[214:215]
	v_lshl_add_u64 v[216:217], v[216:217], 0, v[140:141]
	v_lshl_add_u64 v[218:219], v[216:217], 1, s[76:77]
	v_cvt_pk_bf16_f32 v108, v180, v181
	v_cvt_pk_bf16_f32 v109, v182, v183
	global_store_dwordx2 v[218:219], v[108:109], off
	v_mul_f32_e32 v221, v181, v181
	v_mul_f32_e32 v162, v183, v183
	v_fmac_f32_e32 v221, v180, v180
	v_fmac_f32_e32 v162, v182, v182
	v_add_f32_e32 v220, v221, v162
	v_cvt_pk_bf16_f32 v104, v184, v185
	v_cvt_pk_bf16_f32 v105, v186, v187
	global_store_dwordx2 v[218:219], v[104:105], off offset:32
	v_mul_f32_e32 v221, v185, v185
	v_mul_f32_e32 v162, v187, v187
	v_fmac_f32_e32 v221, v184, v184
	v_fmac_f32_e32 v162, v186, v186
	v_add_f32_e32 v221, v221, v162
	v_add_f32_e32 v220, v220, v221
	v_cvt_pk_bf16_f32 v100, v188, v189
	v_cvt_pk_bf16_f32 v101, v190, v191
	global_store_dwordx2 v[218:219], v[100:101], off offset:256
	v_mul_f32_e32 v221, v189, v189
	v_mul_f32_e32 v162, v191, v191
	v_fmac_f32_e32 v221, v188, v188
	v_fmac_f32_e32 v162, v190, v190
	v_add_f32_e32 v221, v221, v162
	v_add_f32_e32 v220, v220, v221
	v_cvt_pk_bf16_f32 v96, v192, v193
	v_cvt_pk_bf16_f32 v97, v194, v195
	global_store_dwordx2 v[218:219], v[96:97], off offset:288
	v_mul_f32_e32 v221, v193, v193
	v_mul_f32_e32 v162, v195, v195
	v_fmac_f32_e32 v221, v192, v192
	v_fmac_f32_e32 v162, v194, v194
	v_add_f32_e32 v221, v221, v162
	v_add_f32_e32 v164, v220, v221
	v_add_u32_e32 v152, 0x80, v142
	v_ashrrev_i32_e32 v153, 31, v152
	v_lshlrev_b64 v[154:155], 11, v[152:153]
	v_lshl_add_u64 v[154:155], v[154:155], 0, v[140:141]
	v_lshl_add_u64 v[156:157], v[154:155], 2, s[0:1]
	global_load_dwordx4 v[96:99], v[156:157], off
	global_load_dwordx4 v[100:103], v[156:157], off offset:64
	global_load_dwordx4 v[104:107], v[156:157], off offset:512
	global_load_dwordx4 v[108:111], v[156:157], off offset:576
	s_waitcnt vmcnt(16)
; __device__ __forceinline__ unsigned cvt_pk_bf16(float lo, float hi) { unsigned r; asm volatile("v_cvt_pk_bf16_f32 %0, %1, %2" : "=v"(r) : "v"(lo), "v"(hi)); return r; }
;     __device__ __forceinline__ void operator()(const f32x4 (&acc)[2][2][4][2], const Unit& u, int wr, int wc, int fr, int fq) const {
;     ...
;                     for (int n = 0; n < 2; ++n) { f32x4 bs;
;                         if (BASE_BF16) { const u32x2 t = *(const u32x2*)((const bf16_t*)base + off + bj * HALF + n * 16);
;                             bs = (f32x4){__builtin_bit_cast(float, t.x << 16), __builtin_bit_cast(float, t.x & 0xffff0000u), __builtin_bit_cast(float, t.y << 16), __builtin_bit_cast(float, t.y & 0xffff0000u)}; }
;                         else bs = *(const f32x4*)((const float*)base + off + bj * HALF + n * 16);
;                         const f32x4 v = bs + acc[ai][bj][m][n] * scale;
;                         u32x2 w; w.x = cvt_pk_bf16(v[0], v[1]); w.y = cvt_pk_bf16(v[2], v[3]);
;                         *(u32x2*)(xn + off + bj * HALF + n * 16) = w;
;                         ss += (v[0] * v[0] + v[1] * v[1]) + (v[2] * v[2] + v[3] * v[3]); }
	v_pk_fma_f32 v[198:199], v[94:95], 0.5, v[198:199] op_sel_hi:[1,0,1]
	v_pk_fma_f32 v[196:197], v[92:93], 0.5, v[196:197] op_sel_hi:[1,0,1]
	v_pk_fma_f32 v[202:203], v[90:91], 0.5, v[202:203] op_sel_hi:[1,0,1]
	v_pk_fma_f32 v[200:201], v[88:89], 0.5, v[200:201] op_sel_hi:[1,0,1]
	v_pk_fma_f32 v[206:207], v[86:87], 0.5, v[206:207] op_sel_hi:[1,0,1]
	v_pk_fma_f32 v[204:205], v[84:85], 0.5, v[204:205] op_sel_hi:[1,0,1]
	v_pk_fma_f32 v[210:211], v[82:83], 0.5, v[210:211] op_sel_hi:[1,0,1]
	v_pk_fma_f32 v[208:209], v[80:81], 0.5, v[208:209] op_sel_hi:[1,0,1]
	v_add_u32_e32 v214, 32, v142
	v_ashrrev_i32_e32 v215, 31, v214
	v_lshlrev_b64 v[216:217], 11, v[214:215]
	v_lshl_add_u64 v[216:217], v[216:217], 0, v[140:141]
	v_lshl_add_u64 v[218:219], v[216:217], 1, s[76:77]
	v_cvt_pk_bf16_f32 v92, v196, v197
	v_cvt_pk_bf16_f32 v93, v198, v199
	global_store_dwordx2 v[218:219], v[92:93], off
	v_mul_f32_e32 v221, v197, v197
	v_mul_f32_e32 v162, v199, v199
	v_fmac_f32_e32 v221, v196, v196
	v_fmac_f32_e32 v162, v198, v198
	v_add_f32_e32 v220, v221, v162
	v_cvt_pk_bf16_f32 v88, v200, v201
	v_cvt_pk_bf16_f32 v89, v202, v203
	global_store_dwordx2 v[218:219], v[88:89], off offset:32
	v_mul_f32_e32 v221, v201, v201
	v_mul_f32_e32 v162, v203, v203
	v_fmac_f32_e32 v221, v200, v200
	v_fmac_f32_e32 v162, v202, v202
	v_add_f32_e32 v221, v221, v162
	v_add_f32_e32 v220, v220, v221
	v_cvt_pk_bf16_f32 v84, v204, v205
	v_cvt_pk_bf16_f32 v85, v206, v207
	global_store_dwordx2 v[218:219], v[84:85], off offset:256
	v_mul_f32_e32 v221, v205, v205
	v_mul_f32_e32 v162, v207, v207
	v_fmac_f32_e32 v221, v204, v204
	v_fmac_f32_e32 v162, v206, v206
	v_add_f32_e32 v221, v221, v162
	v_add_f32_e32 v220, v220, v221
	v_cvt_pk_bf16_f32 v80, v208, v209
	v_cvt_pk_bf16_f32 v81, v210, v211
	global_store_dwordx2 v[218:219], v[80:81], off offset:288
	v_mul_f32_e32 v221, v209, v209
	v_mul_f32_e32 v162, v211, v211
	v_fmac_f32_e32 v221, v208, v208
	v_fmac_f32_e32 v162, v210, v210
	v_add_f32_e32 v221, v221, v162
	v_add_f32_e32 v165, v220, v221
	v_add_u32_e32 v152, 0x90, v142
	v_ashrrev_i32_e32 v153, 31, v152
	v_lshlrev_b64 v[154:155], 11, v[152:153]
	v_lshl_add_u64 v[154:155], v[154:155], 0, v[140:141]
	v_lshl_add_u64 v[156:157], v[154:155], 2, s[0:1]
	global_load_dwordx4 v[80:83], v[156:157], off
	global_load_dwordx4 v[84:87], v[156:157], off offset:64
	global_load_dwordx4 v[88:91], v[156:157], off offset:512
	global_load_dwordx4 v[92:95], v[156:157], off offset:576
	s_waitcnt vmcnt(16)
	v_pk_fma_f32 v[114:115], v[78:79], 0.5, v[114:115] op_sel_hi:[1,0,1]
	v_pk_fma_f32 v[112:113], v[76:77], 0.5, v[112:113] op_sel_hi:[1,0,1]
	v_pk_fma_f32 v[118:119], v[74:75], 0.5, v[118:119] op_sel_hi:[1,0,1]
	v_pk_fma_f32 v[116:117], v[72:73], 0.5, v[116:117] op_sel_hi:[1,0,1]
	v_pk_fma_f32 v[122:123], v[70:71], 0.5, v[122:123] op_sel_hi:[1,0,1]
	v_pk_fma_f32 v[120:121], v[68:69], 0.5, v[120:121] op_sel_hi:[1,0,1]
	v_pk_fma_f32 v[126:127], v[66:67], 0.5, v[126:127] op_sel_hi:[1,0,1]
	v_pk_fma_f32 v[124:125], v[64:65], 0.5, v[124:125] op_sel_hi:[1,0,1]
	v_add_u32_e32 v214, 48, v142
	v_ashrrev_i32_e32 v215, 31, v214
	v_lshlrev_b64 v[216:217], 11, v[214:215]
	v_lshl_add_u64 v[216:217], v[216:217], 0, v[140:141]
	v_lshl_add_u64 v[218:219], v[216:217], 1, s[76:77]
	v_cvt_pk_bf16_f32 v76, v112, v113
	v_cvt_pk_bf16_f32 v77, v114, v115
	global_store_dwordx2 v[218:219], v[76:77], off
	v_mul_f32_e32 v221, v113, v113
	v_mul_f32_e32 v162, v115, v115
	v_fmac_f32_e32 v221, v112, v112
	v_fmac_f32_e32 v162, v114, v114
	v_add_f32_e32 v220, v221, v162
	v_cvt_pk_bf16_f32 v72, v116, v117
	v_cvt_pk_bf16_f32 v73, v118, v119
	global_store_dwordx2 v[218:219], v[72:73], off offset:32
	v_mul_f32_e32 v221, v117, v117
	v_mul_f32_e32 v162, v119, v119
	v_fmac_f32_e32 v221, v116, v116
	v_fmac_f32_e32 v162, v118, v118
	v_add_f32_e32 v221, v221, v162
	v_add_f32_e32 v220, v220, v221
	v_cvt_pk_bf16_f32 v68, v120, v121
	v_cvt_pk_bf16_f32 v69, v122, v123
	global_store_dwordx2 v[218:219], v[68:69], off offset:256
	v_mul_f32_e32 v221, v121, v121
	v_mul_f32_e32 v162, v123, v123
	v_fmac_f32_e32 v221, v120, v120
	v_fmac_f32_e32 v162, v122, v122
	v_add_f32_e32 v221, v221, v162
	v_add_f32_e32 v220, v220, v221
	v_cvt_pk_bf16_f32 v64, v124, v125
	v_cvt_pk_bf16_f32 v65, v126, v127
	global_store_dwordx2 v[218:219], v[64:65], off offset:288
	v_mul_f32_e32 v221, v125, v125
	v_mul_f32_e32 v162, v127, v127
	v_fmac_f32_e32 v221, v124, v124
	v_fmac_f32_e32 v162, v126, v126
	v_add_f32_e32 v221, v221, v162
	v_add_f32_e32 v166, v220, v221
	v_add_u32_e32 v152, 0xa0, v142
	v_ashrrev_i32_e32 v153, 31, v152
	v_lshlrev_b64 v[154:155], 11, v[152:153]
	v_lshl_add_u64 v[154:155], v[154:155], 0, v[140:141]
	v_lshl_add_u64 v[156:157], v[154:155], 2, s[0:1]
	global_load_dwordx4 v[64:67], v[156:157], off
	global_load_dwordx4 v[68:71], v[156:157], off offset:64
	global_load_dwordx4 v[72:75], v[156:157], off offset:512
	global_load_dwordx4 v[76:79], v[156:157], off offset:576
	s_waitcnt vmcnt(16)
; __device__ __forceinline__ unsigned cvt_pk_bf16(float lo, float hi) { unsigned r; asm volatile("v_cvt_pk_bf16_f32 %0, %1, %2" : "=v"(r) : "v"(lo), "v"(hi)); return r; }
;     __device__ __forceinline__ void operator()(const f32x4 (&acc)[2][2][4][2], const Unit& u, int wr, int wc, int fr, int fq) const {
;     ...
;                     for (int n = 0; n < 2; ++n) { f32x4 bs;
;                         if (BASE_BF16) { const u32x2 t = *(const u32x2*)((const bf16_t*)base + off + bj * HALF + n * 16);
;                             bs = (f32x4){__builtin_bit_cast(float, t.x << 16), __builtin_bit_cast(float, t.x & 0xffff0000u), __builtin_bit_cast(float, t.y << 16), __builtin_bit_cast(float, t.y & 0xffff0000u)}; }
;                         else bs = *(const f32x4*)((const float*)base + off + bj * HALF + n * 16);
;                         const f32x4 v = bs + acc[ai][bj][m][n] * scale;
;                         u32x2 w; w.x = cvt_pk_bf16(v[0], v[1]); w.y = cvt_pk_bf16(v[2], v[3]);
;                         *(u32x2*)(xn + off + bj * HALF + n * 16) = w;
;                         ss += (v[0] * v[0] + v[1] * v[1]) + (v[2] * v[2] + v[3] * v[3]); }
	v_pk_fma_f32 v[98:99], v[62:63], 0.5, v[98:99] op_sel_hi:[1,0,1]
	v_pk_fma_f32 v[96:97], v[60:61], 0.5, v[96:97] op_sel_hi:[1,0,1]
	v_pk_fma_f32 v[102:103], v[58:59], 0.5, v[102:103] op_sel_hi:[1,0,1]
	v_pk_fma_f32 v[100:101], v[56:57], 0.5, v[100:101] op_sel_hi:[1,0,1]
	v_pk_fma_f32 v[106:107], v[54:55], 0.5, v[106:107] op_sel_hi:[1,0,1]
	v_pk_fma_f32 v[104:105], v[52:53], 0.5, v[104:105] op_sel_hi:[1,0,1]
	v_pk_fma_f32 v[110:111], v[50:51], 0.5, v[110:111] op_sel_hi:[1,0,1]
	v_pk_fma_f32 v[108:109], v[48:49], 0.5, v[108:109] op_sel_hi:[1,0,1]
	v_add_u32_e32 v214, 0x80, v142
	v_ashrrev_i32_e32 v215, 31, v214
	v_lshlrev_b64 v[216:217], 11, v[214:215]
	v_lshl_add_u64 v[216:217], v[216:217], 0, v[140:141]
	v_lshl_add_u64 v[218:219], v[216:217], 1, s[76:77]
	v_cvt_pk_bf16_f32 v60, v96, v97
	v_cvt_pk_bf16_f32 v61, v98, v99
	global_store_dwordx2 v[218:219], v[60:61], off
	v_mul_f32_e32 v221, v97, v97
	v_mul_f32_e32 v162, v99, v99
	v_fmac_f32_e32 v221, v96, v96
	v_fmac_f32_e32 v162, v98, v98
	v_add_f32_e32 v220, v221, v162
	v_cvt_pk_bf16_f32 v56, v100, v101
	v_cvt_pk_bf16_f32 v57, v102, v103
	global_store_dwordx2 v[218:219], v[56:57], off offset:32
	v_mul_f32_e32 v221, v101, v101
	v_mul_f32_e32 v162, v103, v103
	v_fmac_f32_e32 v221, v100, v100
	v_fmac_f32_e32 v162, v102, v102
	v_add_f32_e32 v221, v221, v162
	v_add_f32_e32 v220, v220, v221
	v_cvt_pk_bf16_f32 v52, v104, v105
	v_cvt_pk_bf16_f32 v53, v106, v107
	global_store_dwordx2 v[218:219], v[52:53], off offset:256
	v_mul_f32_e32 v221, v105, v105
	v_mul_f32_e32 v162, v107, v107
	v_fmac_f32_e32 v221, v104, v104
	v_fmac_f32_e32 v162, v106, v106
	v_add_f32_e32 v221, v221, v162
	v_add_f32_e32 v220, v220, v221
	v_cvt_pk_bf16_f32 v48, v108, v109
	v_cvt_pk_bf16_f32 v49, v110, v111
	global_store_dwordx2 v[218:219], v[48:49], off offset:288
	v_mul_f32_e32 v221, v109, v109
	v_mul_f32_e32 v162, v111, v111
	v_fmac_f32_e32 v221, v108, v108
	v_fmac_f32_e32 v162, v110, v110
	v_add_f32_e32 v221, v221, v162
	v_add_f32_e32 v167, v220, v221
	v_add_u32_e32 v152, 0xb0, v142
	v_ashrrev_i32_e32 v153, 31, v152
	v_lshlrev_b64 v[154:155], 11, v[152:153]
	v_lshl_add_u64 v[154:155], v[154:155], 0, v[140:141]
	v_lshl_add_u64 v[156:157], v[154:155], 2, s[0:1]
	global_load_dwordx4 v[48:51], v[156:157], off
	global_load_dwordx4 v[52:55], v[156:157], off offset:64
	global_load_dwordx4 v[56:59], v[156:157], off offset:512
	global_load_dwordx4 v[60:63], v[156:157], off offset:576
	s_waitcnt vmcnt(16)
	v_pk_fma_f32 v[82:83], v[46:47], 0.5, v[82:83] op_sel_hi:[1,0,1]
	v_pk_fma_f32 v[80:81], v[44:45], 0.5, v[80:81] op_sel_hi:[1,0,1]
	v_pk_fma_f32 v[86:87], v[42:43], 0.5, v[86:87] op_sel_hi:[1,0,1]
	v_pk_fma_f32 v[84:85], v[40:41], 0.5, v[84:85] op_sel_hi:[1,0,1]
	v_pk_fma_f32 v[90:91], v[38:39], 0.5, v[90:91] op_sel_hi:[1,0,1]
	v_pk_fma_f32 v[88:89], v[36:37], 0.5, v[88:89] op_sel_hi:[1,0,1]
	v_pk_fma_f32 v[94:95], v[34:35], 0.5, v[94:95] op_sel_hi:[1,0,1]
	v_pk_fma_f32 v[92:93], v[32:33], 0.5, v[92:93] op_sel_hi:[1,0,1]
	v_add_u32_e32 v214, 0x90, v142
	v_ashrrev_i32_e32 v215, 31, v214
	v_lshlrev_b64 v[216:217], 11, v[214:215]
	v_lshl_add_u64 v[216:217], v[216:217], 0, v[140:141]
	v_lshl_add_u64 v[218:219], v[216:217], 1, s[76:77]
	v_cvt_pk_bf16_f32 v44, v80, v81
	v_cvt_pk_bf16_f32 v45, v82, v83
	global_store_dwordx2 v[218:219], v[44:45], off
	v_mul_f32_e32 v221, v81, v81
	v_mul_f32_e32 v162, v83, v83
	v_fmac_f32_e32 v221, v80, v80
	v_fmac_f32_e32 v162, v82, v82
	v_add_f32_e32 v220, v221, v162
	v_cvt_pk_bf16_f32 v40, v84, v85
	v_cvt_pk_bf16_f32 v41, v86, v87
	global_store_dwordx2 v[218:219], v[40:41], off offset:32
	v_mul_f32_e32 v221, v85, v85
	v_mul_f32_e32 v162, v87, v87
	v_fmac_f32_e32 v221, v84, v84
	v_fmac_f32_e32 v162, v86, v86
	v_add_f32_e32 v221, v221, v162
	v_add_f32_e32 v220, v220, v221
	v_cvt_pk_bf16_f32 v36, v88, v89
	v_cvt_pk_bf16_f32 v37, v90, v91
	global_store_dwordx2 v[218:219], v[36:37], off offset:256
	v_mul_f32_e32 v221, v89, v89
	v_mul_f32_e32 v162, v91, v91
	v_fmac_f32_e32 v221, v88, v88
	v_fmac_f32_e32 v162, v90, v90
	v_add_f32_e32 v221, v221, v162
	v_add_f32_e32 v220, v220, v221
	v_cvt_pk_bf16_f32 v32, v92, v93
	v_cvt_pk_bf16_f32 v33, v94, v95
	global_store_dwordx2 v[218:219], v[32:33], off offset:288
	v_mul_f32_e32 v221, v93, v93
	v_mul_f32_e32 v162, v95, v95
	v_fmac_f32_e32 v221, v92, v92
	v_fmac_f32_e32 v162, v94, v94
	v_add_f32_e32 v221, v221, v162
	v_add_f32_e32 v168, v220, v221
	s_waitcnt vmcnt(12)
	v_pk_fma_f32 v[66:67], v[30:31], 0.5, v[66:67] op_sel_hi:[1,0,1]
	v_pk_fma_f32 v[64:65], v[28:29], 0.5, v[64:65] op_sel_hi:[1,0,1]
	v_pk_fma_f32 v[70:71], v[26:27], 0.5, v[70:71] op_sel_hi:[1,0,1]
	v_pk_fma_f32 v[68:69], v[24:25], 0.5, v[68:69] op_sel_hi:[1,0,1]
	v_pk_fma_f32 v[74:75], v[22:23], 0.5, v[74:75] op_sel_hi:[1,0,1]
	v_pk_fma_f32 v[72:73], v[20:21], 0.5, v[72:73] op_sel_hi:[1,0,1]
	v_pk_fma_f32 v[78:79], v[18:19], 0.5, v[78:79] op_sel_hi:[1,0,1]
	v_pk_fma_f32 v[76:77], v[16:17], 0.5, v[76:77] op_sel_hi:[1,0,1]
	v_add_u32_e32 v214, 0xa0, v142
	v_ashrrev_i32_e32 v215, 31, v214
	v_lshlrev_b64 v[216:217], 11, v[214:215]
	v_lshl_add_u64 v[216:217], v[216:217], 0, v[140:141]
	v_lshl_add_u64 v[218:219], v[216:217], 1, s[76:77]
	v_cvt_pk_bf16_f32 v28, v64, v65
	v_cvt_pk_bf16_f32 v29, v66, v67
	global_store_dwordx2 v[218:219], v[28:29], off
	v_mul_f32_e32 v221, v65, v65
	v_mul_f32_e32 v162, v67, v67
	v_fmac_f32_e32 v221, v64, v64
	v_fmac_f32_e32 v162, v66, v66
	v_add_f32_e32 v220, v221, v162
	v_cvt_pk_bf16_f32 v24, v68, v69
	v_cvt_pk_bf16_f32 v25, v70, v71
	global_store_dwordx2 v[218:219], v[24:25], off offset:32
	v_mul_f32_e32 v221, v69, v69
	v_mul_f32_e32 v162, v71, v71
	v_fmac_f32_e32 v221, v68, v68
	v_fmac_f32_e32 v162, v70, v70
	v_add_f32_e32 v221, v221, v162
	v_add_f32_e32 v220, v220, v221
	v_cvt_pk_bf16_f32 v20, v72, v73
	v_cvt_pk_bf16_f32 v21, v74, v75
	global_store_dwordx2 v[218:219], v[20:21], off offset:256
	v_mul_f32_e32 v221, v73, v73
	v_mul_f32_e32 v162, v75, v75
	v_fmac_f32_e32 v221, v72, v72
	v_fmac_f32_e32 v162, v74, v74
	v_add_f32_e32 v221, v221, v162
	v_add_f32_e32 v220, v220, v221
	v_cvt_pk_bf16_f32 v16, v76, v77
	v_cvt_pk_bf16_f32 v17, v78, v79
	global_store_dwordx2 v[218:219], v[16:17], off offset:288
	v_mul_f32_e32 v221, v77, v77
	v_mul_f32_e32 v162, v79, v79
	v_fmac_f32_e32 v221, v76, v76
	v_fmac_f32_e32 v162, v78, v78
	v_add_f32_e32 v221, v221, v162
	v_add_f32_e32 v169, v220, v221
	s_waitcnt vmcnt(8)
; __device__ __forceinline__ unsigned cvt_pk_bf16(float lo, float hi) { unsigned r; asm volatile("v_cvt_pk_bf16_f32 %0, %1, %2" : "=v"(r) : "v"(lo), "v"(hi)); return r; }
;     __device__ __forceinline__ void operator()(const f32x4 (&acc)[2][2][4][2], const Unit& u, int wr, int wc, int fr, int fq) const {
;     ...
;                     for (int n = 0; n < 2; ++n) { f32x4 bs;
;                         if (BASE_BF16) { const u32x2 t = *(const u32x2*)((const bf16_t*)base + off + bj * HALF + n * 16);
;                             bs = (f32x4){__builtin_bit_cast(float, t.x << 16), __builtin_bit_cast(float, t.x & 0xffff0000u), __builtin_bit_cast(float, t.y << 16), __builtin_bit_cast(float, t.y & 0xffff0000u)}; }
;                         else bs = *(const f32x4*)((const float*)base + off + bj * HALF + n * 16);
;                         const f32x4 v = bs + acc[ai][bj][m][n] * scale;
;                         u32x2 w; w.x = cvt_pk_bf16(v[0], v[1]); w.y = cvt_pk_bf16(v[2], v[3]);
;                         *(u32x2*)(xn + off + bj * HALF + n * 16) = w;
;                         ss += (v[0] * v[0] + v[1] * v[1]) + (v[2] * v[2] + v[3] * v[3]); }
;                 ss += __shfl_xor(ss, 16); ss += __shfl_xor(ss, 32);
;                 if (fq == 0) __hip_atomic_fetch_add(rowss + row, ss, __ATOMIC_RELAXED, __HIP_MEMORY_SCOPE_AGENT); }
	v_pk_fma_f32 v[50:51], v[14:15], 0.5, v[50:51] op_sel_hi:[1,0,1]
	v_pk_fma_f32 v[48:49], v[12:13], 0.5, v[48:49] op_sel_hi:[1,0,1]
	v_pk_fma_f32 v[54:55], v[10:11], 0.5, v[54:55] op_sel_hi:[1,0,1]
	v_pk_fma_f32 v[52:53], v[8:9], 0.5, v[52:53] op_sel_hi:[1,0,1]
	v_pk_fma_f32 v[58:59], v[6:7], 0.5, v[58:59] op_sel_hi:[1,0,1]
	v_pk_fma_f32 v[56:57], v[4:5], 0.5, v[56:57] op_sel_hi:[1,0,1]
	v_pk_fma_f32 v[62:63], v[2:3], 0.5, v[62:63] op_sel_hi:[1,0,1]
	v_pk_fma_f32 v[60:61], v[0:1], 0.5, v[60:61] op_sel_hi:[1,0,1]
	v_add_u32_e32 v214, 0xb0, v142
	v_ashrrev_i32_e32 v215, 31, v214
	v_lshlrev_b64 v[216:217], 11, v[214:215]
	v_lshl_add_u64 v[216:217], v[216:217], 0, v[140:141]
	v_lshl_add_u64 v[218:219], v[216:217], 1, s[76:77]
	v_cvt_pk_bf16_f32 v12, v48, v49
	v_cvt_pk_bf16_f32 v13, v50, v51
	global_store_dwordx2 v[218:219], v[12:13], off
	v_mul_f32_e32 v221, v49, v49
	v_mul_f32_e32 v162, v51, v51
	v_fmac_f32_e32 v221, v48, v48
	v_fmac_f32_e32 v162, v50, v50
	v_add_f32_e32 v220, v221, v162
	v_cvt_pk_bf16_f32 v8, v52, v53
	v_cvt_pk_bf16_f32 v9, v54, v55
	global_store_dwordx2 v[218:219], v[8:9], off offset:32
	v_mul_f32_e32 v221, v53, v53
	v_mul_f32_e32 v162, v55, v55
	v_fmac_f32_e32 v221, v52, v52
	v_fmac_f32_e32 v162, v54, v54
	v_add_f32_e32 v221, v221, v162
	v_add_f32_e32 v220, v220, v221
	v_cvt_pk_bf16_f32 v4, v56, v57
	v_cvt_pk_bf16_f32 v5, v58, v59
	global_store_dwordx2 v[218:219], v[4:5], off offset:256
	v_mul_f32_e32 v221, v57, v57
	v_mul_f32_e32 v162, v59, v59
	v_fmac_f32_e32 v221, v56, v56
	v_fmac_f32_e32 v162, v58, v58
	v_add_f32_e32 v221, v221, v162
	v_add_f32_e32 v220, v220, v221
	v_cvt_pk_bf16_f32 v0, v60, v61
	v_cvt_pk_bf16_f32 v1, v62, v63
	global_store_dwordx2 v[218:219], v[0:1], off offset:288
	v_mul_f32_e32 v221, v61, v61
	v_mul_f32_e32 v162, v63, v63
	v_fmac_f32_e32 v221, v60, v60
	v_fmac_f32_e32 v162, v62, v62
	v_add_f32_e32 v221, v221, v162
	v_add_f32_e32 v170, v220, v221
	ds_bpermute_b32 v172, v212, v160
	ds_bpermute_b32 v173, v212, v164
	ds_bpermute_b32 v174, v212, v165
	ds_bpermute_b32 v175, v212, v166
	ds_bpermute_b32 v176, v212, v167
	ds_bpermute_b32 v177, v212, v168
	ds_bpermute_b32 v178, v212, v169
	ds_bpermute_b32 v179, v212, v170
	s_waitcnt lgkmcnt(0)
	v_add_f32_e32 v160, v160, v172
	v_add_f32_e32 v164, v164, v173
	v_add_f32_e32 v165, v165, v174
	v_add_f32_e32 v166, v166, v175
	v_add_f32_e32 v167, v167, v176
	v_add_f32_e32 v168, v168, v177
	v_add_f32_e32 v169, v169, v178
	v_add_f32_e32 v170, v170, v179
	ds_bpermute_b32 v172, v213, v160
	ds_bpermute_b32 v173, v213, v164
	ds_bpermute_b32 v174, v213, v165
	ds_bpermute_b32 v175, v213, v166
	ds_bpermute_b32 v176, v213, v167
	ds_bpermute_b32 v177, v213, v168
	ds_bpermute_b32 v178, v213, v169
	ds_bpermute_b32 v179, v213, v170
	s_waitcnt lgkmcnt(0)
	v_add_f32_e32 v160, v160, v172
	v_add_f32_e32 v164, v164, v173
	v_add_f32_e32 v165, v165, v174
	v_add_f32_e32 v166, v166, v175
	v_add_f32_e32 v167, v167, v176
	v_add_f32_e32 v168, v168, v177
	v_add_f32_e32 v169, v169, v178
	v_add_f32_e32 v170, v170, v179
	v_mul_f32_e32 v160, 0x43000000, v160
	v_mul_f32_e32 v164, 0x43000000, v164
	v_mul_f32_e32 v165, 0x43000000, v165
	v_mul_f32_e32 v166, 0x43000000, v166
	v_mul_f32_e32 v167, 0x43000000, v167
	v_mul_f32_e32 v168, 0x43000000, v168
	v_mul_f32_e32 v169, 0x43000000, v169
	v_mul_f32_e32 v170, 0x43000000, v170
	v_rndne_f32_e32 v160, v160
	v_rndne_f32_e32 v164, v164
	v_rndne_f32_e32 v165, v165
	v_rndne_f32_e32 v166, v166
	v_rndne_f32_e32 v167, v167
	v_rndne_f32_e32 v168, v168
	v_rndne_f32_e32 v169, v169
	v_rndne_f32_e32 v170, v170
	v_mul_f32_e32 v160, 0x3c000000, v160
	v_mul_f32_e32 v164, 0x3c000000, v164
	v_mul_f32_e32 v165, 0x3c000000, v165
	v_mul_f32_e32 v166, 0x3c000000, v166
	v_mul_f32_e32 v167, 0x3c000000, v167
	v_mul_f32_e32 v168, 0x3c000000, v168
	v_mul_f32_e32 v169, 0x3c000000, v169
	v_mul_f32_e32 v170, 0x3c000000, v170
	s_and_saveexec_b64 s[26:27], s[6:7]
	v_mov_b32_e32 v214, v142
	v_ashrrev_i32_e32 v215, 31, v214
	v_lshl_add_u64 v[216:217], v[214:215], 2, s[16:17]
	global_atomic_add_f32 v[216:217], v160, off
	v_add_u32_e32 v214, 16, v142
	v_ashrrev_i32_e32 v215, 31, v214
	v_lshl_add_u64 v[216:217], v[214:215], 2, s[16:17]
	global_atomic_add_f32 v[216:217], v164, off
	v_add_u32_e32 v214, 32, v142
	v_ashrrev_i32_e32 v215, 31, v214
	v_lshl_add_u64 v[216:217], v[214:215], 2, s[16:17]
	global_atomic_add_f32 v[216:217], v165, off
	v_add_u32_e32 v214, 48, v142
	v_ashrrev_i32_e32 v215, 31, v214
	v_lshl_add_u64 v[216:217], v[214:215], 2, s[16:17]
	global_atomic_add_f32 v[216:217], v166, off
	v_add_u32_e32 v214, 0x80, v142
	v_ashrrev_i32_e32 v215, 31, v214
	v_lshl_add_u64 v[216:217], v[214:215], 2, s[16:17]
	global_atomic_add_f32 v[216:217], v167, off
	v_add_u32_e32 v214, 0x90, v142
	v_ashrrev_i32_e32 v215, 31, v214
	v_lshl_add_u64 v[216:217], v[214:215], 2, s[16:17]
	global_atomic_add_f32 v[216:217], v168, off
	v_add_u32_e32 v214, 0xa0, v142
	v_ashrrev_i32_e32 v215, 31, v214
	v_lshl_add_u64 v[216:217], v[214:215], 2, s[16:17]
	global_atomic_add_f32 v[216:217], v169, off
	v_add_u32_e32 v214, 0xb0, v142
	v_ashrrev_i32_e32 v215, 31, v214
	v_lshl_add_u64 v[216:217], v[214:215], 2, s[16:17]
	global_atomic_add_f32 v[216:217], v170, off
	s_or_b64 exec, exec, s[26:27]
	s_and_b64 vcc, exec, s[8:9]
	s_mov_b64 s[8:9], -1
	s_cbranch_vccnz .LBB0_295
	s_andn2_b64 vcc, exec, s[2:3]
	s_cbranch_vccnz .LBB0_294
	s_barrier
	s_branch .LBB0_294

; __device__ __forceinline__ unsigned cvt_pk_bf16(float lo, float hi) { unsigned r; asm volatile("v_cvt_pk_bf16_f32 %0, %1, %2" : "=v"(r) : "v"(lo), "v"(hi)); return r; }
;     __device__ __forceinline__ void operator()(const f32x4 (&acc)[2][2][4][2], const Unit& u, int wr, int wc, int fr, int fq) const {
;     ...
;             for (int m = 0; m < 4; ++m) { const int row = u.pm * BM + ai * HALF + wr * 64 + m * 16 + fr; const size_t off = (size_t)row * ldc + col0;
;                 float ss = 0.f;
; #pragma unroll
;                 for (int bj = 0; bj < 2; ++bj)
; #pragma unroll
;                     for (int n = 0; n < 2; ++n) { f32x4 bs;
;                         if (BASE_BF16) { const u32x2 t = *(const u32x2*)((const bf16_t*)base + off + bj * HALF + n * 16);
;                             bs = (f32x4){__builtin_bit_cast(float, t.x << 16), __builtin_bit_cast(float, t.x & 0xffff0000u), __builtin_bit_cast(float, t.y << 16), __builtin_bit_cast(float, t.y & 0xffff0000u)}; }
;                         else bs = *(const f32x4*)((const float*)base + off + bj * HALF + n * 16);
;                         const f32x4 v = bs + acc[ai][bj][m][n] * scale;
;                         u32x2 w; w.x = cvt_pk_bf16(v[0], v[1]); w.y = cvt_pk_bf16(v[2], v[3]);
;                         *(u32x2*)(xn + off + bj * HALF + n * 16) = w;
;                         ss += (v[0] * v[0] + v[1] * v[1]) + (v[2] * v[2] + v[3] * v[3]); }
.LBB0_848:
	s_waitcnt vmcnt(24)
	v_mov_b32_e32 v140, v143
	v_lshlrev_b32_e32 v216, 16, v152
	v_and_b32_e32 v217, 0xffff0000, v152
	v_lshlrev_b32_e32 v218, 16, v153
	v_and_b32_e32 v219, 0xffff0000, v153
	v_pk_add_f32 v[124:125], v[124:125], v[216:217]
	v_pk_add_f32 v[126:127], v[126:127], v[218:219]
	v_cvt_pk_bf16_f32 v152, v124, v125
	v_cvt_pk_bf16_f32 v153, v126, v127
	global_store_dwordx2 v140, v[152:153], s[68:69]
	v_mul_f32_e32 v220, v125, v125
	v_mul_f32_e32 v221, v127, v127
	v_fmac_f32_e32 v220, v124, v124
	v_fmac_f32_e32 v221, v126, v126
	v_add_f32_e32 v208, v220, v221
	v_lshlrev_b32_e32 v216, 16, v154
	v_and_b32_e32 v217, 0xffff0000, v154
	v_lshlrev_b32_e32 v218, 16, v155
	v_and_b32_e32 v219, 0xffff0000, v155
	v_pk_add_f32 v[120:121], v[120:121], v[216:217]
	v_pk_add_f32 v[122:123], v[122:123], v[218:219]
	v_cvt_pk_bf16_f32 v154, v120, v121
	v_cvt_pk_bf16_f32 v155, v122, v123
	global_store_dwordx2 v140, v[154:155], s[68:69] offset:32
	v_mul_f32_e32 v220, v121, v121
	v_mul_f32_e32 v221, v123, v123
	v_fmac_f32_e32 v220, v120, v120
	v_fmac_f32_e32 v221, v122, v122
	v_add_f32_e32 v220, v220, v221
	v_add_f32_e32 v208, v208, v220
	v_lshlrev_b32_e32 v216, 16, v156
	v_and_b32_e32 v217, 0xffff0000, v156
	v_lshlrev_b32_e32 v218, 16, v157
	v_and_b32_e32 v219, 0xffff0000, v157
	v_pk_add_f32 v[116:117], v[116:117], v[216:217]
	v_pk_add_f32 v[118:119], v[118:119], v[218:219]
	v_cvt_pk_bf16_f32 v156, v116, v117
	v_cvt_pk_bf16_f32 v157, v118, v119
	global_store_dwordx2 v140, v[156:157], s[68:69] offset:256
	v_mul_f32_e32 v220, v117, v117
	v_mul_f32_e32 v221, v119, v119
	v_fmac_f32_e32 v220, v116, v116
	v_fmac_f32_e32 v221, v118, v118
	v_add_f32_e32 v220, v220, v221
	v_add_f32_e32 v208, v208, v220
	v_lshlrev_b32_e32 v216, 16, v158
	v_and_b32_e32 v217, 0xffff0000, v158
	v_lshlrev_b32_e32 v218, 16, v159
	v_and_b32_e32 v219, 0xffff0000, v159
	v_pk_add_f32 v[112:113], v[112:113], v[216:217]
	v_pk_add_f32 v[114:115], v[114:115], v[218:219]
	v_cvt_pk_bf16_f32 v158, v112, v113
	v_cvt_pk_bf16_f32 v159, v114, v115
	global_store_dwordx2 v140, v[158:159], s[68:69] offset:288
	v_mul_f32_e32 v220, v113, v113
	v_mul_f32_e32 v221, v115, v115
	v_fmac_f32_e32 v220, v112, v112
	v_fmac_f32_e32 v221, v114, v114
	v_add_f32_e32 v220, v220, v221
	v_add_f32_e32 v208, v208, v220
	v_add_u32_e32 v140, 0xb0000, v143
	global_load_dwordx2 v[152:153], v140, s[76:77]
	global_load_dwordx2 v[154:155], v140, s[76:77] offset:32
	global_load_dwordx2 v[156:157], v140, s[76:77] offset:256
	global_load_dwordx2 v[158:159], v140, s[76:77] offset:288
	s_waitcnt vmcnt(28)
	v_add_u32_e32 v140, 0x10000, v143
	v_lshlrev_b32_e32 v216, 16, v160
	v_and_b32_e32 v217, 0xffff0000, v160
	v_lshlrev_b32_e32 v218, 16, v161
	v_and_b32_e32 v219, 0xffff0000, v161
	v_pk_add_f32 v[108:109], v[108:109], v[216:217]
	v_pk_add_f32 v[110:111], v[110:111], v[218:219]
	v_cvt_pk_bf16_f32 v160, v108, v109
	v_cvt_pk_bf16_f32 v161, v110, v111
	global_store_dwordx2 v140, v[160:161], s[68:69]
	v_mul_f32_e32 v220, v109, v109
	v_mul_f32_e32 v221, v111, v111
	v_fmac_f32_e32 v220, v108, v108
	v_fmac_f32_e32 v221, v110, v110
	v_add_f32_e32 v209, v220, v221
	v_lshlrev_b32_e32 v216, 16, v162
	v_and_b32_e32 v217, 0xffff0000, v162
	v_lshlrev_b32_e32 v218, 16, v163
	v_and_b32_e32 v219, 0xffff0000, v163
	v_pk_add_f32 v[104:105], v[104:105], v[216:217]
	v_pk_add_f32 v[106:107], v[106:107], v[218:219]
	v_cvt_pk_bf16_f32 v162, v104, v105
	v_cvt_pk_bf16_f32 v163, v106, v107
	global_store_dwordx2 v140, v[162:163], s[68:69] offset:32
	v_mul_f32_e32 v220, v105, v105
	v_mul_f32_e32 v221, v107, v107
	v_fmac_f32_e32 v220, v104, v104
	v_fmac_f32_e32 v221, v106, v106
	v_add_f32_e32 v220, v220, v221
	v_add_f32_e32 v209, v209, v220
	v_lshlrev_b32_e32 v216, 16, v164
	v_and_b32_e32 v217, 0xffff0000, v164
	v_lshlrev_b32_e32 v218, 16, v165
	v_and_b32_e32 v219, 0xffff0000, v165
	v_pk_add_f32 v[100:101], v[100:101], v[216:217]
	v_pk_add_f32 v[102:103], v[102:103], v[218:219]
	v_cvt_pk_bf16_f32 v164, v100, v101
	v_cvt_pk_bf16_f32 v165, v102, v103
	global_store_dwordx2 v140, v[164:165], s[68:69] offset:256
	v_mul_f32_e32 v220, v101, v101
	v_mul_f32_e32 v221, v103, v103
	v_fmac_f32_e32 v220, v100, v100
	v_fmac_f32_e32 v221, v102, v102
	v_add_f32_e32 v220, v220, v221
	v_add_f32_e32 v209, v209, v220
	v_lshlrev_b32_e32 v216, 16, v166
	v_and_b32_e32 v217, 0xffff0000, v166
	v_lshlrev_b32_e32 v218, 16, v167
	v_and_b32_e32 v219, 0xffff0000, v167
	v_pk_add_f32 v[96:97], v[96:97], v[216:217]
	v_pk_add_f32 v[98:99], v[98:99], v[218:219]
	v_cvt_pk_bf16_f32 v166, v96, v97
	v_cvt_pk_bf16_f32 v167, v98, v99
	global_store_dwordx2 v140, v[166:167], s[68:69] offset:288
	v_mul_f32_e32 v220, v97, v97
	v_mul_f32_e32 v221, v99, v99
	v_fmac_f32_e32 v220, v96, v96
	v_fmac_f32_e32 v221, v98, v98
	v_add_f32_e32 v220, v220, v221
	v_add_f32_e32 v209, v209, v220
	s_waitcnt vmcnt(28)
; __device__ __forceinline__ unsigned cvt_pk_bf16(float lo, float hi) { unsigned r; asm volatile("v_cvt_pk_bf16_f32 %0, %1, %2" : "=v"(r) : "v"(lo), "v"(hi)); return r; }
;     __device__ __forceinline__ void operator()(const f32x4 (&acc)[2][2][4][2], const Unit& u, int wr, int wc, int fr, int fq) const {
;     ...
;             for (int m = 0; m < 4; ++m) { const int row = u.pm * BM + ai * HALF + wr * 64 + m * 16 + fr; const size_t off = (size_t)row * ldc + col0;
;                 float ss = 0.f;
; #pragma unroll
;                 for (int bj = 0; bj < 2; ++bj)
; #pragma unroll
;                     for (int n = 0; n < 2; ++n) { f32x4 bs;
;                         if (BASE_BF16) { const u32x2 t = *(const u32x2*)((const bf16_t*)base + off + bj * HALF + n * 16);
;                             bs = (f32x4){__builtin_bit_cast(float, t.x << 16), __builtin_bit_cast(float, t.x & 0xffff0000u), __builtin_bit_cast(float, t.y << 16), __builtin_bit_cast(float, t.y & 0xffff0000u)}; }
;                         else bs = *(const f32x4*)((const float*)base + off + bj * HALF + n * 16);
;                         const f32x4 v = bs + acc[ai][bj][m][n] * scale;
;                         u32x2 w; w.x = cvt_pk_bf16(v[0], v[1]); w.y = cvt_pk_bf16(v[2], v[3]);
;                         *(u32x2*)(xn + off + bj * HALF + n * 16) = w;
;                         ss += (v[0] * v[0] + v[1] * v[1]) + (v[2] * v[2] + v[3] * v[3]); }
	v_add_u32_e32 v140, 0x20000, v143
	v_lshlrev_b32_e32 v216, 16, v168
	v_and_b32_e32 v217, 0xffff0000, v168
	v_lshlrev_b32_e32 v218, 16, v169
	v_and_b32_e32 v219, 0xffff0000, v169
	v_pk_add_f32 v[92:93], v[92:93], v[216:217]
	v_pk_add_f32 v[94:95], v[94:95], v[218:219]
	v_cvt_pk_bf16_f32 v168, v92, v93
	v_cvt_pk_bf16_f32 v169, v94, v95
	global_store_dwordx2 v140, v[168:169], s[68:69]
	v_mul_f32_e32 v220, v93, v93
	v_mul_f32_e32 v221, v95, v95
	v_fmac_f32_e32 v220, v92, v92
	v_fmac_f32_e32 v221, v94, v94
	v_add_f32_e32 v210, v220, v221
	v_lshlrev_b32_e32 v216, 16, v170
	v_and_b32_e32 v217, 0xffff0000, v170
	v_lshlrev_b32_e32 v218, 16, v171
	v_and_b32_e32 v219, 0xffff0000, v171
	v_pk_add_f32 v[88:89], v[88:89], v[216:217]
	v_pk_add_f32 v[90:91], v[90:91], v[218:219]
	v_cvt_pk_bf16_f32 v170, v88, v89
	v_cvt_pk_bf16_f32 v171, v90, v91
	global_store_dwordx2 v140, v[170:171], s[68:69] offset:32
	v_mul_f32_e32 v220, v89, v89
	v_mul_f32_e32 v221, v91, v91
	v_fmac_f32_e32 v220, v88, v88
	v_fmac_f32_e32 v221, v90, v90
	v_add_f32_e32 v220, v220, v221
	v_add_f32_e32 v210, v210, v220
	v_lshlrev_b32_e32 v216, 16, v172
	v_and_b32_e32 v217, 0xffff0000, v172
	v_lshlrev_b32_e32 v218, 16, v173
	v_and_b32_e32 v219, 0xffff0000, v173
	v_pk_add_f32 v[84:85], v[84:85], v[216:217]
	v_pk_add_f32 v[86:87], v[86:87], v[218:219]
	v_cvt_pk_bf16_f32 v172, v84, v85
	v_cvt_pk_bf16_f32 v173, v86, v87
	global_store_dwordx2 v140, v[172:173], s[68:69] offset:256
	v_mul_f32_e32 v220, v85, v85
	v_mul_f32_e32 v221, v87, v87
	v_fmac_f32_e32 v220, v84, v84
	v_fmac_f32_e32 v221, v86, v86
	v_add_f32_e32 v220, v220, v221
	v_add_f32_e32 v210, v210, v220
	v_lshlrev_b32_e32 v216, 16, v174
	v_and_b32_e32 v217, 0xffff0000, v174
	v_lshlrev_b32_e32 v218, 16, v175
	v_and_b32_e32 v219, 0xffff0000, v175
	v_pk_add_f32 v[80:81], v[80:81], v[216:217]
	v_pk_add_f32 v[82:83], v[82:83], v[218:219]
	v_cvt_pk_bf16_f32 v174, v80, v81
	v_cvt_pk_bf16_f32 v175, v82, v83
	global_store_dwordx2 v140, v[174:175], s[68:69] offset:288
	v_mul_f32_e32 v220, v81, v81
	v_mul_f32_e32 v221, v83, v83
	v_fmac_f32_e32 v220, v80, v80
	v_fmac_f32_e32 v221, v82, v82
	v_add_f32_e32 v220, v220, v221
	v_add_f32_e32 v210, v210, v220
	s_waitcnt vmcnt(28)
	v_add_u32_e32 v140, 0x30000, v143
	v_lshlrev_b32_e32 v216, 16, v176
	v_and_b32_e32 v217, 0xffff0000, v176
	v_lshlrev_b32_e32 v218, 16, v177
	v_and_b32_e32 v219, 0xffff0000, v177
	v_pk_add_f32 v[76:77], v[76:77], v[216:217]
	v_pk_add_f32 v[78:79], v[78:79], v[218:219]
	v_cvt_pk_bf16_f32 v176, v76, v77
	v_cvt_pk_bf16_f32 v177, v78, v79
	global_store_dwordx2 v140, v[176:177], s[68:69]
	v_mul_f32_e32 v220, v77, v77
	v_mul_f32_e32 v221, v79, v79
	v_fmac_f32_e32 v220, v76, v76
	v_fmac_f32_e32 v221, v78, v78
	v_add_f32_e32 v211, v220, v221
	v_lshlrev_b32_e32 v216, 16, v178
	v_and_b32_e32 v217, 0xffff0000, v178
	v_lshlrev_b32_e32 v218, 16, v179
	v_and_b32_e32 v219, 0xffff0000, v179
	v_pk_add_f32 v[72:73], v[72:73], v[216:217]
	v_pk_add_f32 v[74:75], v[74:75], v[218:219]
	v_cvt_pk_bf16_f32 v178, v72, v73
	v_cvt_pk_bf16_f32 v179, v74, v75
	global_store_dwordx2 v140, v[178:179], s[68:69] offset:32
	v_mul_f32_e32 v220, v73, v73
	v_mul_f32_e32 v221, v75, v75
	v_fmac_f32_e32 v220, v72, v72
	v_fmac_f32_e32 v221, v74, v74
	v_add_f32_e32 v220, v220, v221
	v_add_f32_e32 v211, v211, v220
	v_lshlrev_b32_e32 v216, 16, v180
	v_and_b32_e32 v217, 0xffff0000, v180
	v_lshlrev_b32_e32 v218, 16, v181
	v_and_b32_e32 v219, 0xffff0000, v181
	v_pk_add_f32 v[68:69], v[68:69], v[216:217]
	v_pk_add_f32 v[70:71], v[70:71], v[218:219]
	v_cvt_pk_bf16_f32 v180, v68, v69
	v_cvt_pk_bf16_f32 v181, v70, v71
	global_store_dwordx2 v140, v[180:181], s[68:69] offset:256
	v_mul_f32_e32 v220, v69, v69
	v_mul_f32_e32 v221, v71, v71
	v_fmac_f32_e32 v220, v68, v68
	v_fmac_f32_e32 v221, v70, v70
	v_add_f32_e32 v220, v220, v221
	v_add_f32_e32 v211, v211, v220
	v_lshlrev_b32_e32 v216, 16, v182
	v_and_b32_e32 v217, 0xffff0000, v182
	v_lshlrev_b32_e32 v218, 16, v183
	v_and_b32_e32 v219, 0xffff0000, v183
	v_pk_add_f32 v[64:65], v[64:65], v[216:217]
	v_pk_add_f32 v[66:67], v[66:67], v[218:219]
	v_cvt_pk_bf16_f32 v182, v64, v65
	v_cvt_pk_bf16_f32 v183, v66, v67
	global_store_dwordx2 v140, v[182:183], s[68:69] offset:288
	v_mul_f32_e32 v220, v65, v65
	v_mul_f32_e32 v221, v67, v67
	v_fmac_f32_e32 v220, v64, v64
	v_fmac_f32_e32 v221, v66, v66
	v_add_f32_e32 v220, v220, v221
	v_add_f32_e32 v211, v211, v220
	s_waitcnt vmcnt(28)
	v_add_u32_e32 v140, 0x80000, v143
	v_lshlrev_b32_e32 v216, 16, v184
	v_and_b32_e32 v217, 0xffff0000, v184
	v_lshlrev_b32_e32 v218, 16, v185
	v_and_b32_e32 v219, 0xffff0000, v185
	v_pk_add_f32 v[60:61], v[60:61], v[216:217]
	v_pk_add_f32 v[62:63], v[62:63], v[218:219]
	v_cvt_pk_bf16_f32 v184, v60, v61
	v_cvt_pk_bf16_f32 v185, v62, v63
	global_store_dwordx2 v140, v[184:185], s[68:69]
	v_mul_f32_e32 v220, v61, v61
	v_mul_f32_e32 v221, v63, v63
	v_fmac_f32_e32 v220, v60, v60
	v_fmac_f32_e32 v221, v62, v62
	v_add_f32_e32 v212, v220, v221
	v_lshlrev_b32_e32 v216, 16, v186
	v_and_b32_e32 v217, 0xffff0000, v186
	v_lshlrev_b32_e32 v218, 16, v187
	v_and_b32_e32 v219, 0xffff0000, v187
	v_pk_add_f32 v[56:57], v[56:57], v[216:217]
	v_pk_add_f32 v[58:59], v[58:59], v[218:219]
	v_cvt_pk_bf16_f32 v186, v56, v57
	v_cvt_pk_bf16_f32 v187, v58, v59
	global_store_dwordx2 v140, v[186:187], s[68:69] offset:32
	v_mul_f32_e32 v220, v57, v57
	v_mul_f32_e32 v221, v59, v59
	v_fmac_f32_e32 v220, v56, v56
	v_fmac_f32_e32 v221, v58, v58
	v_add_f32_e32 v220, v220, v221
	v_add_f32_e32 v212, v212, v220
	v_lshlrev_b32_e32 v216, 16, v188
	v_and_b32_e32 v217, 0xffff0000, v188
	v_lshlrev_b32_e32 v218, 16, v189
	v_and_b32_e32 v219, 0xffff0000, v189
	v_pk_add_f32 v[52:53], v[52:53], v[216:217]
	v_pk_add_f32 v[54:55], v[54:55], v[218:219]
	v_cvt_pk_bf16_f32 v188, v52, v53
	v_cvt_pk_bf16_f32 v189, v54, v55
	global_store_dwordx2 v140, v[188:189], s[68:69] offset:256
	v_mul_f32_e32 v220, v53, v53
	v_mul_f32_e32 v221, v55, v55
	v_fmac_f32_e32 v220, v52, v52
	v_fmac_f32_e32 v221, v54, v54
	v_add_f32_e32 v220, v220, v221
	v_add_f32_e32 v212, v212, v220
	v_lshlrev_b32_e32 v216, 16, v190
	v_and_b32_e32 v217, 0xffff0000, v190
	v_lshlrev_b32_e32 v218, 16, v191
	v_and_b32_e32 v219, 0xffff0000, v191
	v_pk_add_f32 v[48:49], v[48:49], v[216:217]
	v_pk_add_f32 v[50:51], v[50:51], v[218:219]
	v_cvt_pk_bf16_f32 v190, v48, v49
	v_cvt_pk_bf16_f32 v191, v50, v51
	global_store_dwordx2 v140, v[190:191], s[68:69] offset:288
	v_mul_f32_e32 v220, v49, v49
	v_mul_f32_e32 v221, v51, v51
	v_fmac_f32_e32 v220, v48, v48
	v_fmac_f32_e32 v221, v50, v50
	v_add_f32_e32 v220, v220, v221
	v_add_f32_e32 v212, v212, v220
	s_waitcnt vmcnt(28)
; __device__ __forceinline__ unsigned cvt_pk_bf16(float lo, float hi) { unsigned r; asm volatile("v_cvt_pk_bf16_f32 %0, %1, %2" : "=v"(r) : "v"(lo), "v"(hi)); return r; }
;     __device__ __forceinline__ void operator()(const f32x4 (&acc)[2][2][4][2], const Unit& u, int wr, int wc, int fr, int fq) const {
;     ...
;             for (int m = 0; m < 4; ++m) { const int row = u.pm * BM + ai * HALF + wr * 64 + m * 16 + fr; const size_t off = (size_t)row * ldc + col0;
;                 float ss = 0.f;
; #pragma unroll
;                 for (int bj = 0; bj < 2; ++bj)
; #pragma unroll
;                     for (int n = 0; n < 2; ++n) { f32x4 bs;
;                         if (BASE_BF16) { const u32x2 t = *(const u32x2*)((const bf16_t*)base + off + bj * HALF + n * 16);
;                             bs = (f32x4){__builtin_bit_cast(float, t.x << 16), __builtin_bit_cast(float, t.x & 0xffff0000u), __builtin_bit_cast(float, t.y << 16), __builtin_bit_cast(float, t.y & 0xffff0000u)}; }
;                         else bs = *(const f32x4*)((const float*)base + off + bj * HALF + n * 16);
;                         const f32x4 v = bs + acc[ai][bj][m][n] * scale;
;                         u32x2 w; w.x = cvt_pk_bf16(v[0], v[1]); w.y = cvt_pk_bf16(v[2], v[3]);
;                         *(u32x2*)(xn + off + bj * HALF + n * 16) = w;
;                         ss += (v[0] * v[0] + v[1] * v[1]) + (v[2] * v[2] + v[3] * v[3]); }
	v_add_u32_e32 v140, 0x90000, v143
	v_lshlrev_b32_e32 v216, 16, v192
	v_and_b32_e32 v217, 0xffff0000, v192
	v_lshlrev_b32_e32 v218, 16, v193
	v_and_b32_e32 v219, 0xffff0000, v193
	v_pk_add_f32 v[44:45], v[44:45], v[216:217]
	v_pk_add_f32 v[46:47], v[46:47], v[218:219]
	v_cvt_pk_bf16_f32 v192, v44, v45
	v_cvt_pk_bf16_f32 v193, v46, v47
	global_store_dwordx2 v140, v[192:193], s[68:69]
	v_mul_f32_e32 v220, v45, v45
	v_mul_f32_e32 v221, v47, v47
	v_fmac_f32_e32 v220, v44, v44
	v_fmac_f32_e32 v221, v46, v46
	v_add_f32_e32 v213, v220, v221
	v_lshlrev_b32_e32 v216, 16, v194
	v_and_b32_e32 v217, 0xffff0000, v194
	v_lshlrev_b32_e32 v218, 16, v195
	v_and_b32_e32 v219, 0xffff0000, v195
	v_pk_add_f32 v[40:41], v[40:41], v[216:217]
	v_pk_add_f32 v[42:43], v[42:43], v[218:219]
	v_cvt_pk_bf16_f32 v194, v40, v41
	v_cvt_pk_bf16_f32 v195, v42, v43
	global_store_dwordx2 v140, v[194:195], s[68:69] offset:32
	v_mul_f32_e32 v220, v41, v41
	v_mul_f32_e32 v221, v43, v43
	v_fmac_f32_e32 v220, v40, v40
	v_fmac_f32_e32 v221, v42, v42
	v_add_f32_e32 v220, v220, v221
	v_add_f32_e32 v213, v213, v220
	v_lshlrev_b32_e32 v216, 16, v196
	v_and_b32_e32 v217, 0xffff0000, v196
	v_lshlrev_b32_e32 v218, 16, v197
	v_and_b32_e32 v219, 0xffff0000, v197
	v_pk_add_f32 v[36:37], v[36:37], v[216:217]
	v_pk_add_f32 v[38:39], v[38:39], v[218:219]
	v_cvt_pk_bf16_f32 v196, v36, v37
	v_cvt_pk_bf16_f32 v197, v38, v39
	global_store_dwordx2 v140, v[196:197], s[68:69] offset:256
	v_mul_f32_e32 v220, v37, v37
	v_mul_f32_e32 v221, v39, v39
	v_fmac_f32_e32 v220, v36, v36
	v_fmac_f32_e32 v221, v38, v38
	v_add_f32_e32 v220, v220, v221
	v_add_f32_e32 v213, v213, v220
	v_lshlrev_b32_e32 v216, 16, v198
	v_and_b32_e32 v217, 0xffff0000, v198
	v_lshlrev_b32_e32 v218, 16, v199
	v_and_b32_e32 v219, 0xffff0000, v199
	v_pk_add_f32 v[32:33], v[32:33], v[216:217]
	v_pk_add_f32 v[34:35], v[34:35], v[218:219]
	v_cvt_pk_bf16_f32 v198, v32, v33
	v_cvt_pk_bf16_f32 v199, v34, v35
	global_store_dwordx2 v140, v[198:199], s[68:69] offset:288
	v_mul_f32_e32 v220, v33, v33
	v_mul_f32_e32 v221, v35, v35
	v_fmac_f32_e32 v220, v32, v32
	v_fmac_f32_e32 v221, v34, v34
	v_add_f32_e32 v220, v220, v221
	v_add_f32_e32 v213, v213, v220
	s_waitcnt vmcnt(28)
	v_add_u32_e32 v140, 0xa0000, v143
	v_lshlrev_b32_e32 v216, 16, v200
	v_and_b32_e32 v217, 0xffff0000, v200
	v_lshlrev_b32_e32 v218, 16, v201
	v_and_b32_e32 v219, 0xffff0000, v201
	v_pk_add_f32 v[28:29], v[28:29], v[216:217]
	v_pk_add_f32 v[30:31], v[30:31], v[218:219]
	v_cvt_pk_bf16_f32 v200, v28, v29
	v_cvt_pk_bf16_f32 v201, v30, v31
	global_store_dwordx2 v140, v[200:201], s[68:69]
	v_mul_f32_e32 v220, v29, v29
	v_mul_f32_e32 v221, v31, v31
	v_fmac_f32_e32 v220, v28, v28
	v_fmac_f32_e32 v221, v30, v30
	v_add_f32_e32 v214, v220, v221
	v_lshlrev_b32_e32 v216, 16, v202
	v_and_b32_e32 v217, 0xffff0000, v202
	v_lshlrev_b32_e32 v218, 16, v203
	v_and_b32_e32 v219, 0xffff0000, v203
	v_pk_add_f32 v[24:25], v[24:25], v[216:217]
	v_pk_add_f32 v[26:27], v[26:27], v[218:219]
	v_cvt_pk_bf16_f32 v202, v24, v25
	v_cvt_pk_bf16_f32 v203, v26, v27
	global_store_dwordx2 v140, v[202:203], s[68:69] offset:32
	v_mul_f32_e32 v220, v25, v25
	v_mul_f32_e32 v221, v27, v27
	v_fmac_f32_e32 v220, v24, v24
	v_fmac_f32_e32 v221, v26, v26
	v_add_f32_e32 v220, v220, v221
	v_add_f32_e32 v214, v214, v220
	v_lshlrev_b32_e32 v216, 16, v204
	v_and_b32_e32 v217, 0xffff0000, v204
	v_lshlrev_b32_e32 v218, 16, v205
	v_and_b32_e32 v219, 0xffff0000, v205
	v_pk_add_f32 v[20:21], v[20:21], v[216:217]
	v_pk_add_f32 v[22:23], v[22:23], v[218:219]
	v_cvt_pk_bf16_f32 v204, v20, v21
	v_cvt_pk_bf16_f32 v205, v22, v23
	global_store_dwordx2 v140, v[204:205], s[68:69] offset:256
	v_mul_f32_e32 v220, v21, v21
	v_mul_f32_e32 v221, v23, v23
	v_fmac_f32_e32 v220, v20, v20
	v_fmac_f32_e32 v221, v22, v22
	v_add_f32_e32 v220, v220, v221
	v_add_f32_e32 v214, v214, v220
	v_lshlrev_b32_e32 v216, 16, v206
	v_and_b32_e32 v217, 0xffff0000, v206
	v_lshlrev_b32_e32 v218, 16, v207
	v_and_b32_e32 v219, 0xffff0000, v207
	v_pk_add_f32 v[16:17], v[16:17], v[216:217]
	v_pk_add_f32 v[18:19], v[18:19], v[218:219]
	v_cvt_pk_bf16_f32 v206, v16, v17
	v_cvt_pk_bf16_f32 v207, v18, v19
	global_store_dwordx2 v140, v[206:207], s[68:69] offset:288
	v_mul_f32_e32 v220, v17, v17
	v_mul_f32_e32 v221, v19, v19
	v_fmac_f32_e32 v220, v16, v16
	v_fmac_f32_e32 v221, v18, v18
	v_add_f32_e32 v220, v220, v221
	v_add_f32_e32 v214, v214, v220
	s_waitcnt vmcnt(24)
; __device__ __forceinline__ unsigned cvt_pk_bf16(float lo, float hi) { unsigned r; asm volatile("v_cvt_pk_bf16_f32 %0, %1, %2" : "=v"(r) : "v"(lo), "v"(hi)); return r; }
;     __device__ __forceinline__ void operator()(const f32x4 (&acc)[2][2][4][2], const Unit& u, int wr, int wc, int fr, int fq) const {
;     ...
;                     for (int n = 0; n < 2; ++n) { f32x4 bs;
;                         if (BASE_BF16) { const u32x2 t = *(const u32x2*)((const bf16_t*)base + off + bj * HALF + n * 16);
;                             bs = (f32x4){__builtin_bit_cast(float, t.x << 16), __builtin_bit_cast(float, t.x & 0xffff0000u), __builtin_bit_cast(float, t.y << 16), __builtin_bit_cast(float, t.y & 0xffff0000u)}; }
;                         else bs = *(const f32x4*)((const float*)base + off + bj * HALF + n * 16);
;                         const f32x4 v = bs + acc[ai][bj][m][n] * scale;
;                         u32x2 w; w.x = cvt_pk_bf16(v[0], v[1]); w.y = cvt_pk_bf16(v[2], v[3]);
;                         *(u32x2*)(xn + off + bj * HALF + n * 16) = w;
;                         ss += (v[0] * v[0] + v[1] * v[1]) + (v[2] * v[2] + v[3] * v[3]); }
;                 ss += __shfl_xor(ss, 16); ss += __shfl_xor(ss, 32);
;                 if (fq == 0) __hip_atomic_fetch_add(rowss + row, ss, __ATOMIC_RELAXED, __HIP_MEMORY_SCOPE_AGENT); }
	v_add_u32_e32 v140, 0xb0000, v143
	v_lshlrev_b32_e32 v216, 16, v152
	v_and_b32_e32 v217, 0xffff0000, v152
	v_lshlrev_b32_e32 v218, 16, v153
	v_and_b32_e32 v219, 0xffff0000, v153
	v_pk_add_f32 v[12:13], v[12:13], v[216:217]
	v_pk_add_f32 v[14:15], v[14:15], v[218:219]
	v_cvt_pk_bf16_f32 v152, v12, v13
	v_cvt_pk_bf16_f32 v153, v14, v15
	global_store_dwordx2 v140, v[152:153], s[68:69]
	v_mul_f32_e32 v220, v13, v13
	v_mul_f32_e32 v221, v15, v15
	v_fmac_f32_e32 v220, v12, v12
	v_fmac_f32_e32 v221, v14, v14
	v_add_f32_e32 v215, v220, v221
	v_lshlrev_b32_e32 v216, 16, v154
	v_and_b32_e32 v217, 0xffff0000, v154
	v_lshlrev_b32_e32 v218, 16, v155
	v_and_b32_e32 v219, 0xffff0000, v155
	v_pk_add_f32 v[8:9], v[8:9], v[216:217]
	v_pk_add_f32 v[10:11], v[10:11], v[218:219]
	v_cvt_pk_bf16_f32 v154, v8, v9
	v_cvt_pk_bf16_f32 v155, v10, v11
	global_store_dwordx2 v140, v[154:155], s[68:69] offset:32
	v_mul_f32_e32 v220, v9, v9
	v_mul_f32_e32 v221, v11, v11
	v_fmac_f32_e32 v220, v8, v8
	v_fmac_f32_e32 v221, v10, v10
	v_add_f32_e32 v220, v220, v221
	v_add_f32_e32 v215, v215, v220
	v_lshlrev_b32_e32 v216, 16, v156
	v_and_b32_e32 v217, 0xffff0000, v156
	v_lshlrev_b32_e32 v218, 16, v157
	v_and_b32_e32 v219, 0xffff0000, v157
	v_pk_add_f32 v[4:5], v[4:5], v[216:217]
	v_pk_add_f32 v[6:7], v[6:7], v[218:219]
	v_cvt_pk_bf16_f32 v156, v4, v5
	v_cvt_pk_bf16_f32 v157, v6, v7
	global_store_dwordx2 v140, v[156:157], s[68:69] offset:256
	v_mul_f32_e32 v220, v5, v5
	v_mul_f32_e32 v221, v7, v7
	v_fmac_f32_e32 v220, v4, v4
	v_fmac_f32_e32 v221, v6, v6
	v_add_f32_e32 v220, v220, v221
	v_add_f32_e32 v215, v215, v220
	v_lshlrev_b32_e32 v216, 16, v158
	v_and_b32_e32 v217, 0xffff0000, v158
	v_lshlrev_b32_e32 v218, 16, v159
	v_and_b32_e32 v219, 0xffff0000, v159
	v_pk_add_f32 v[0:1], v[0:1], v[216:217]
	v_pk_add_f32 v[2:3], v[2:3], v[218:219]
	v_cvt_pk_bf16_f32 v158, v0, v1
	v_cvt_pk_bf16_f32 v159, v2, v3
	global_store_dwordx2 v140, v[158:159], s[68:69] offset:288
	v_mul_f32_e32 v220, v1, v1
	v_mul_f32_e32 v221, v3, v3
	v_fmac_f32_e32 v220, v0, v0
	v_fmac_f32_e32 v221, v2, v2
	v_add_f32_e32 v220, v220, v221
	v_add_f32_e32 v215, v215, v220
	ds_bpermute_b32 v160, v151, v208
	ds_bpermute_b32 v161, v151, v209
	ds_bpermute_b32 v162, v151, v210
	ds_bpermute_b32 v163, v151, v211
	ds_bpermute_b32 v164, v151, v212
	ds_bpermute_b32 v165, v151, v213
	ds_bpermute_b32 v166, v151, v214
	ds_bpermute_b32 v167, v151, v215
	s_waitcnt lgkmcnt(0)
	v_add_f32_e32 v208, v208, v160
	v_add_f32_e32 v209, v209, v161
	v_add_f32_e32 v210, v210, v162
	v_add_f32_e32 v211, v211, v163
	v_add_f32_e32 v212, v212, v164
	v_add_f32_e32 v213, v213, v165
	v_add_f32_e32 v214, v214, v166
	v_add_f32_e32 v215, v215, v167
	ds_bpermute_b32 v160, v141, v208
	ds_bpermute_b32 v161, v141, v209
	ds_bpermute_b32 v162, v141, v210
	ds_bpermute_b32 v163, v141, v211
	ds_bpermute_b32 v164, v141, v212
	ds_bpermute_b32 v165, v141, v213
	ds_bpermute_b32 v166, v141, v214
	ds_bpermute_b32 v167, v141, v215
	s_waitcnt lgkmcnt(0)
	v_add_f32_e32 v208, v208, v160
	v_add_f32_e32 v209, v209, v161
	v_add_f32_e32 v210, v210, v162
	v_add_f32_e32 v211, v211, v163
	v_add_f32_e32 v212, v212, v164
	v_add_f32_e32 v213, v213, v165
	v_add_f32_e32 v214, v214, v166
	v_add_f32_e32 v215, v215, v167
	v_mul_f32_e32 v208, 0x43000000, v208
	v_mul_f32_e32 v209, 0x43000000, v209
	v_mul_f32_e32 v210, 0x43000000, v210
	v_mul_f32_e32 v211, 0x43000000, v211
	v_mul_f32_e32 v212, 0x43000000, v212
	v_mul_f32_e32 v213, 0x43000000, v213
	v_mul_f32_e32 v214, 0x43000000, v214
	v_mul_f32_e32 v215, 0x43000000, v215
	v_rndne_f32_e32 v208, v208
	v_rndne_f32_e32 v209, v209
	v_rndne_f32_e32 v210, v210
	v_rndne_f32_e32 v211, v211
	v_rndne_f32_e32 v212, v212
	v_rndne_f32_e32 v213, v213
	v_rndne_f32_e32 v214, v214
	v_rndne_f32_e32 v215, v215
	v_mul_f32_e32 v208, 0x3c000000, v208
	v_mul_f32_e32 v209, 0x3c000000, v209
	v_mul_f32_e32 v210, 0x3c000000, v210
	v_mul_f32_e32 v211, 0x3c000000, v211
	v_mul_f32_e32 v212, 0x3c000000, v212
	v_mul_f32_e32 v213, 0x3c000000, v213
	v_mul_f32_e32 v214, 0x3c000000, v214
	v_mul_f32_e32 v215, 0x3c000000, v215
	s_and_saveexec_b64 s[20:21], s[6:7]
	v_mov_b32_e32 v140, v142
	global_atomic_add_f32 v140, v208, s[10:11]
	v_add_u32_e32 v140, 0x40, v142
	global_atomic_add_f32 v140, v209, s[10:11]
	v_add_u32_e32 v140, 0x80, v142
	global_atomic_add_f32 v140, v210, s[10:11]
	v_add_u32_e32 v140, 0xc0, v142
	global_atomic_add_f32 v140, v211, s[10:11]
	v_add_u32_e32 v140, 0x200, v142
	global_atomic_add_f32 v140, v212, s[10:11]
	v_add_u32_e32 v140, 0x240, v142
	global_atomic_add_f32 v140, v213, s[10:11]
	v_add_u32_e32 v140, 0x280, v142
	global_atomic_add_f32 v140, v214, s[10:11]
	v_add_u32_e32 v140, 0x2c0, v142
	global_atomic_add_f32 v140, v215, s[10:11]
	s_or_b64 exec, exec, s[20:21]
	s_andn2_b64 vcc, exec, s[8:9]
	s_mov_b64 s[8:9], -1
	s_cbranch_vccnz .LBB0_837
	s_andn2_b64 vcc, exec, s[0:1]
	s_cbranch_vccnz .LBB0_836
	s_barrier
	s_branch .LBB0_836
